# tr1 plus scan tail read batching, xor-32 permlane swaps and leader-path trim combined
# speedup vs baseline: 1.0180x; 1.0037x over previous
; __device__ __forceinline__ unsigned cvt_pk(float lo, float hi) { unsigned r; asm volatile("v_cvt_pk_bf16_f32 %0, %1, %2" : "=v"(r) : "v"(lo), "v"(hi)); return r; }
; template <int SPLIT> __device__ __forceinline__ void scan_item(const Params& p, unsigned char* smem, const int item, const int vh) {
;     ...
;             const float m_old = sc[0], M127 = sc[1];
;             const float decay = __expf(m_old - M127);
;             {
;                 const f32x4 a4 = *(const f32x4*)(a_s + sp * 4);
;                 float wsv[4];
; #pragma unroll
;                 for (int i = 0; i < 4; ++i) wsv[i] = __expf(a4[i] - M127);
; #pragma unroll
;                 for (int i = 0; i < 4; ++i) { const u32x4 k = kreg[i]; u32x4 w;
;                     w.x = cvt_pk(bflo(k.x) * wsv[i], bfhi(k.x) * wsv[i]); w.y = cvt_pk(bflo(k.y) * wsv[i], bfhi(k.y) * wsv[i]);
;                     w.z = cvt_pk(bflo(k.z) * wsv[i], bfhi(k.z) * wsv[i]); w.w = cvt_pk(bflo(k.w) * wsv[i], bfhi(k.w) * wsv[i]);
;                     *(u32x4*)(KP + swz(sp * 4 + i, ch)) = w; }
; #pragma unroll
;                 for (int e2 = 0; e2 < 4; ++e2) {
;                     const unsigned k0 = kreg[0][e2], k1 = kreg[1][e2], k2 = kreg[2][e2], k3 = kreg[3][e2];
;                     const unsigned v0 = vreg[0][e2], v1 = vreg[1][e2], v2 = vreg[2][e2], v3 = vreg[3][e2];
;                     const int d0 = ch * 8 + 2 * e2, d1 = d0 + 1; const int co = (sp & 1) * 8;
;                     u32x2 o;
;                     o.x = cvt_pk(bflo(k0) * wsv[0], bflo(k1) * wsv[1]); o.y = cvt_pk(bflo(k2) * wsv[2], bflo(k3) * wsv[3]);
;                     *(u32x2*)(KT + swz(d0, sp >> 1) + co) = o;
;                     o.x = cvt_pk(bfhi(k0) * wsv[0], bfhi(k1) * wsv[1]); o.y = cvt_pk(bfhi(k2) * wsv[2], bfhi(k3) * wsv[3]);
;                     *(u32x2*)(KT + swz(d1, sp >> 1) + co) = o;
;                     o.x = (v0 & 0xffffu) | (v1 << 16); o.y = (v2 & 0xffffu) | (v3 << 16);
;                     *(u32x2*)(VT + swz(d0, sp >> 1) + co) = o;
;                     o.x = (v0 >> 16) | (v1 & 0xffff0000u); o.y = (v2 >> 16) | (v3 & 0xffff0000u);
;                     *(u32x2*)(VT + swz(d1, sp >> 1) + co) = o;
;                 }
;             }
;             const size_t rowl = (size_t)(rfirst + rstep * (j * 128 + wid * 16 + li));
;             __syncthreads();
.LBB0_316:
	s_or_b64 exec, exec, s[86:87]
	v_mov_b32_e32 v67, s92
	s_waitcnt lgkmcnt(0)
	s_barrier
	ds_read_b64 v[86:87], v67
	ds_read_b128 v[88:91], v98
	s_waitcnt vmcnt(11)
	v_lshlrev_b32_e32 v92, 16, v45
	v_and_b32_e32 v45, 0xffff0000, v45
	v_lshlrev_b32_e32 v94, 16, v46
	v_and_b32_e32 v46, 0xffff0000, v46
	s_waitcnt lgkmcnt(0)
	v_sub_f32_e32 v67, v88, v87
	v_mul_f32_e32 v67, 0x3fb8aa3b, v67
	v_exp_f32_e32 v67, v67
	v_sub_f32_e32 v84, v89, v87
	v_mul_f32_e32 v84, 0x3fb8aa3b, v84
	v_exp_f32_e32 v84, v84
	v_sub_f32_e32 v88, v90, v87
	v_mul_f32_e32 v88, 0x3fb8aa3b, v88
	v_lshlrev_b32_e32 v90, 16, v44
	v_and_b32_e32 v44, 0xffff0000, v44
	v_exp_f32_e32 v88, v88
	v_sub_f32_e32 v89, v91, v87
	v_mul_f32_e32 v90, v67, v90
	v_mul_f32_e32 v91, v67, v44
	v_cvt_pk_bf16_f32 v44, v90, v91
	v_mul_f32_e32 v92, v67, v92
	v_mul_f32_e32 v93, v67, v45
	v_cvt_pk_bf16_f32 v45, v92, v93
	v_mul_f32_e32 v94, v67, v94
	v_mul_f32_e32 v95, v67, v46
	v_cvt_pk_bf16_f32 v46, v94, v95
	v_lshlrev_b32_e32 v151, 16, v47
	v_and_b32_e32 v47, 0xffff0000, v47
	v_mul_f32_e32 v89, 0x3fb8aa3b, v89
	v_mul_f32_e32 v151, v67, v151
	v_mul_f32_e32 v67, v67, v47
	v_cvt_pk_bf16_f32 v47, v151, v67
	ds_write_b128 v133, v[44:47]
	s_waitcnt vmcnt(10)
	v_lshlrev_b32_e32 v44, 16, v40
	v_and_b32_e32 v40, 0xffff0000, v40
	v_lshlrev_b32_e32 v46, 16, v41
	v_and_b32_e32 v41, 0xffff0000, v41
	v_lshlrev_b32_e32 v152, 16, v42
	v_and_b32_e32 v42, 0xffff0000, v42
	v_exp_f32_e32 v89, v89
	v_mul_f32_e32 v44, v84, v44
	v_mul_f32_e32 v45, v84, v40
	v_cvt_pk_bf16_f32 v40, v44, v45
	v_mul_f32_e32 v46, v84, v46
	v_mul_f32_e32 v47, v84, v41
	v_cvt_pk_bf16_f32 v41, v46, v47
	v_mul_f32_e32 v152, v84, v152
	v_mul_f32_e32 v153, v84, v42
	v_cvt_pk_bf16_f32 v42, v152, v153
	v_lshlrev_b32_e32 v154, 16, v43
	v_and_b32_e32 v43, 0xffff0000, v43
	v_mul_f32_e32 v154, v84, v154
	v_mul_f32_e32 v84, v84, v43
	v_cvt_pk_bf16_f32 v43, v154, v84
	ds_write_b128 v134, v[40:43]
	s_waitcnt vmcnt(9)
	v_lshlrev_b32_e32 v40, 16, v36
	v_and_b32_e32 v36, 0xffff0000, v36
	v_lshlrev_b32_e32 v42, 16, v37
	v_and_b32_e32 v37, 0xffff0000, v37
	v_lshlrev_b32_e32 v155, 16, v38
	v_and_b32_e32 v38, 0xffff0000, v38
	v_mul_f32_e32 v40, v88, v40
	v_mul_f32_e32 v41, v88, v36
	v_cvt_pk_bf16_f32 v36, v40, v41
	v_mul_f32_e32 v42, v88, v42
	v_mul_f32_e32 v43, v88, v37
	v_cvt_pk_bf16_f32 v37, v42, v43
	v_mul_f32_e32 v155, v88, v155
	v_mul_f32_e32 v156, v88, v38
	v_cvt_pk_bf16_f32 v38, v155, v156
	v_lshlrev_b32_e32 v157, 16, v39
	v_and_b32_e32 v39, 0xffff0000, v39
	v_mul_f32_e32 v157, v88, v157
	v_mul_f32_e32 v88, v88, v39
	v_cvt_pk_bf16_f32 v39, v157, v88
	ds_write_b128 v135, v[36:39]
	s_waitcnt vmcnt(7)
	v_lshlrev_b32_e32 v36, 16, v32
	v_and_b32_e32 v32, 0xffff0000, v32
	v_lshlrev_b32_e32 v38, 16, v33
	v_and_b32_e32 v33, 0xffff0000, v33
	v_lshlrev_b32_e32 v158, 16, v34
	v_and_b32_e32 v34, 0xffff0000, v34
	v_mul_f32_e32 v36, v89, v36
	v_mul_f32_e32 v37, v89, v32
	v_cvt_pk_bf16_f32 v32, v36, v37
	v_mul_f32_e32 v38, v89, v38
	v_mul_f32_e32 v39, v89, v33
	v_cvt_pk_bf16_f32 v33, v38, v39
	v_mul_f32_e32 v158, v89, v158
	v_mul_f32_e32 v159, v89, v34
	v_cvt_pk_bf16_f32 v34, v158, v159
	v_lshlrev_b32_e32 v160, 16, v35
	v_and_b32_e32 v35, 0xffff0000, v35
	v_mul_f32_e32 v160, v89, v160
	v_mul_f32_e32 v89, v89, v35
	v_cvt_pk_bf16_f32 v35, v160, v89
	ds_write_b128 v136, v[32:35]
	v_cvt_pk_bf16_f32 v32, v90, v44
	v_cvt_pk_bf16_f32 v33, v40, v36
	v_add_u32_e32 v34, v102, v123
	ds_write_b64 v34, v[32:33]
	v_cvt_pk_bf16_f32 v32, v91, v45
	v_cvt_pk_bf16_f32 v33, v41, v37
	v_add_u32_e32 v34, v102, v124
	ds_write_b64 v34, v[32:33]
	s_waitcnt vmcnt(4)
	v_lshlrev_b32_e32 v32, 16, v4
	v_lshlrev_b32_e32 v33, 16, v16
	v_and_or_b32 v32, v0, s95, v32
	v_and_or_b32 v33, v8, s95, v33
	v_add_u32_e32 v34, v103, v123
	v_lshrrev_b32_e32 v0, 16, v0
	ds_write_b64 v34, v[32:33] offset:32768
	v_and_or_b32 v32, v4, s94, v0
	v_lshrrev_b32_e32 v0, 16, v8
	v_and_or_b32 v33, v16, s94, v0
	v_add_u32_e32 v0, v103, v124
	ds_write_b64 v0, v[32:33] offset:32768
	v_add_u32_e32 v0, v102, v125
	v_cvt_pk_bf16_f32 v32, v92, v46
	v_cvt_pk_bf16_f32 v33, v42, v38
	ds_write_b64 v0, v[32:33]
	v_add_u32_e32 v0, v102, v126
	v_cvt_pk_bf16_f32 v32, v93, v47
	v_cvt_pk_bf16_f32 v33, v43, v39
	ds_write_b64 v0, v[32:33]
	v_lshlrev_b32_e32 v0, 16, v5
	v_and_or_b32 v32, v1, s95, v0
	v_lshlrev_b32_e32 v0, 16, v17
	v_and_or_b32 v33, v9, s95, v0
	v_add_u32_e32 v0, v103, v125
	ds_write_b64 v0, v[32:33] offset:32768
	v_lshrrev_b32_e32 v0, 16, v1
	v_lshrrev_b32_e32 v1, 16, v9
	v_and_or_b32 v0, v5, s94, v0
	v_and_or_b32 v1, v17, s94, v1
	v_add_u32_e32 v4, v103, v126
	ds_write_b64 v4, v[0:1] offset:32768
	v_cvt_pk_bf16_f32 v0, v94, v152
	v_cvt_pk_bf16_f32 v1, v155, v158
	v_add_u32_e32 v4, v102, v127
	ds_write_b64 v4, v[0:1]
	v_cvt_pk_bf16_f32 v0, v95, v153
	v_cvt_pk_bf16_f32 v1, v156, v159
	v_add_u32_e32 v4, v102, v128
	ds_write_b64 v4, v[0:1]
	v_lshlrev_b32_e32 v0, 16, v6
	v_lshlrev_b32_e32 v1, 16, v18
	v_and_or_b32 v0, v2, s95, v0
	v_and_or_b32 v1, v10, s95, v1
	v_add_u32_e32 v4, v103, v127
	ds_write_b64 v4, v[0:1] offset:32768
	v_lshrrev_b32_e32 v0, 16, v2
	v_lshrrev_b32_e32 v1, 16, v10
	v_and_or_b32 v0, v6, s94, v0
	v_and_or_b32 v1, v18, s94, v1
	v_add_u32_e32 v2, v103, v128
	ds_write_b64 v2, v[0:1] offset:32768
	v_cvt_pk_bf16_f32 v0, v151, v154
	v_cvt_pk_bf16_f32 v1, v157, v160
	v_add_u32_e32 v2, v102, v129
	ds_write_b64 v2, v[0:1]
	v_cvt_pk_bf16_f32 v0, v67, v84
	v_cvt_pk_bf16_f32 v1, v88, v89
	v_add_u32_e32 v2, v102, v130
	ds_write_b64 v2, v[0:1]
	v_lshlrev_b32_e32 v0, 16, v7
	v_lshlrev_b32_e32 v1, 16, v19
	v_and_or_b32 v0, v3, s95, v0
	v_and_or_b32 v1, v11, s95, v1
	v_add_u32_e32 v2, v103, v129
	ds_write_b64 v2, v[0:1] offset:32768
	v_lshrrev_b32_e32 v0, 16, v3
	v_lshrrev_b32_e32 v1, 16, v11
	v_and_or_b32 v0, v7, s94, v0
	v_and_or_b32 v1, v19, s94, v1
	v_add_u32_e32 v2, v103, v130
	s_lshl_b32 s0, vcc_lo, 7
	ds_write_b64 v2, v[0:1] offset:32768
	v_or_b32_e32 v0, s0, v85
	v_mul_lo_u32 v0, v0, s3
	v_add_u32_e32 v4, s33, v0
	v_ashrrev_i32_e32 v5, 31, v4
	v_lshlrev_b64 v[0:1], 10, v[4:5]
	v_add_u32_e32 v8, s3, v4
	v_lshl_add_u64 v[0:1], v[64:65], 0, v[0:1]
	v_ashrrev_i32_e32 v9, 31, v8
	s_waitcnt lgkmcnt(0)
	s_barrier
; #define SCAN_LOAD(j) do { \
;         _Pragma("unroll") for (int i = 0; i < 4; ++i) { const size_t r = (size_t)(rfirst + rstep * ((j) * 128 + sp * 4 + i)); \
;             kreg[i] = *(const u32x4*)(K0 + r * 512 + h * 128 + ch * 8); vreg[i] = *(const u32x4*)(P0 + r * LDP + 1536 + h * 128 + ch * 8); } \
;         } while (0)
; template <int SPLIT> __device__ __forceinline__ void scan_item(const Params& p, unsigned char* smem, const int item, const int vh) {
;     ...
;             SCAN_LOAD(jn);
;             __builtin_amdgcn_sched_barrier(0);
;             const int l = wid * 16 + li;
;             const float Ml = M_s[l], gl = g_s[l];
;             f32x4 acc[8];
; #pragma unroll
;             for (int nb = 0; nb < 8; ++nb) acc[nb] = (f32x4){0.f, 0.f, 0.f, 0.f};
;             mm16<8>(acc, KP, qf, lane);
;             __builtin_amdgcn_sched_barrier(0);
;             float rs = 0.f; u32x2 pp[8];
;             const float rowf = __expf(fminf(sc[1] - Ml, 80.f));
	global_load_dwordx4 v[44:47], v[0:1], off
	v_mad_i64_i32 v[0:1], s[4:5], v4, s88, v[80:81]
	v_lshlrev_b64 v[4:5], 10, v[8:9]
	v_add_u32_e32 v16, s3, v8
	v_lshl_add_u64 v[4:5], v[64:65], 0, v[4:5]
	v_ashrrev_i32_e32 v17, 31, v16
	global_load_dwordx4 v[40:43], v[4:5], off
	v_mad_i64_i32 v[4:5], s[4:5], v8, s88, v[80:81]
	v_lshlrev_b64 v[8:9], 10, v[16:17]
	v_lshl_add_u64 v[8:9], v[64:65], 0, v[8:9]
	global_load_dwordx4 v[36:39], v[8:9], off
	v_mad_i64_i32 v[8:9], s[4:5], v16, s88, v[80:81]
	v_add_u32_e32 v16, s3, v16
	v_ashrrev_i32_e32 v17, 31, v16
	v_lshlrev_b64 v[18:19], 10, v[16:17]
	v_lshl_add_u64 v[18:19], v[64:65], 0, v[18:19]
	v_mad_i64_i32 v[16:17], s[4:5], v16, s88, v[80:81]
	global_load_dwordx4 v[0:3], v[0:1], off offset:3072
	v_sub_f32_e32 v67, v86, v87
	global_load_dwordx4 v[4:7], v[4:5], off offset:3072
	v_mul_f32_e32 v67, 0x3fb8aa3b, v67
	global_load_dwordx4 v[8:11], v[8:9], off offset:3072
	v_exp_f32_e32 v84, v67
	global_load_dwordx4 v[32:35], v[18:19], off
	s_nop 0
	global_load_dwordx4 v[16:19], v[16:17], off offset:3072
	v_add_u32_e32 v67, 0, v107
	ds_read_b128 v[88:91], v67
	ds_read_b128 v[92:95], v67 offset:4096
	ds_read_b32 v151, v105
	ds_read_b128 v[152:155], v67 offset:8192
	ds_read_b128 v[156:159], v67 offset:12288
	ds_read_b32 v171, v104
	s_waitcnt vmcnt(11) lgkmcnt(5)
	v_mfma_f32_16x16x32_bf16 v[88:91], v[88:91], v[28:31], 0
	s_waitcnt lgkmcnt(4)
	v_mfma_f32_16x16x32_bf16 v[92:95], v[92:95], v[28:31], 0
	s_waitcnt lgkmcnt(2)
	v_mfma_f32_16x16x32_bf16 v[152:155], v[152:155], v[28:31], 0
	s_waitcnt lgkmcnt(1)
	v_mfma_f32_16x16x32_bf16 v[156:159], v[156:159], v[28:31], 0
	ds_read_b128 v[160:163], v67 offset:16384
	ds_read_b128 v[164:167], v67 offset:20480
	ds_read_b128 v[172:175], v67 offset:24576
	ds_read_b128 v[178:181], v67 offset:28672
	s_waitcnt lgkmcnt(3)
	v_mfma_f32_16x16x32_bf16 v[160:163], v[160:163], v[28:31], 0
	s_waitcnt lgkmcnt(2)
	v_mfma_f32_16x16x32_bf16 v[164:167], v[164:167], v[28:31], 0
	s_waitcnt lgkmcnt(1)
	v_mfma_f32_16x16x32_bf16 v[172:175], v[172:175], v[28:31], 0
	s_waitcnt lgkmcnt(0)
	v_mfma_f32_16x16x32_bf16 v[178:181], v[178:181], v[28:31], 0
	v_add_u32_e32 v246, 0, v109
	ds_read_b128 v[218:221], v246
	ds_read_b128 v[222:225], v246 offset:4096
	ds_read_b128 v[226:229], v246 offset:8192
	ds_read_b128 v[230:233], v246 offset:12288
	ds_read_b128 v[234:237], v246 offset:16384
	v_add_u32_e32 v67, 0, v109
	ds_read_b128 v[238:241], v246 offset:20480
	s_waitcnt vmcnt(10) lgkmcnt(5)
	v_mfma_f32_16x16x32_bf16 v[88:91], v[218:221], v[24:27], v[88:91]
	ds_read_b128 v[218:221], v246 offset:24576
	s_waitcnt lgkmcnt(5)
	v_mfma_f32_16x16x32_bf16 v[92:95], v[222:225], v[24:27], v[92:95]
	ds_read_b128 v[222:225], v246 offset:28672
	s_waitcnt lgkmcnt(5)
	v_mfma_f32_16x16x32_bf16 v[152:155], v[226:229], v[24:27], v[152:155]
	v_add_u32_e32 v247, 0, v111
	ds_read_b128 v[226:229], v247
	s_waitcnt lgkmcnt(5)
	v_mfma_f32_16x16x32_bf16 v[156:159], v[230:233], v[24:27], v[156:159]
	ds_read_b128 v[230:233], v247 offset:4096
	s_waitcnt lgkmcnt(5)
	v_mfma_f32_16x16x32_bf16 v[160:163], v[234:237], v[24:27], v[160:163]
	ds_read_b128 v[234:237], v247 offset:8192
	s_waitcnt lgkmcnt(5)
	v_mfma_f32_16x16x32_bf16 v[164:167], v[238:241], v[24:27], v[164:167]
	ds_read_b128 v[238:241], v247 offset:12288
	s_waitcnt lgkmcnt(5)
	v_mfma_f32_16x16x32_bf16 v[172:175], v[218:221], v[24:27], v[172:175]
	ds_read_b128 v[218:221], v247 offset:16384
	s_waitcnt lgkmcnt(5)
	v_mfma_f32_16x16x32_bf16 v[178:181], v[222:225], v[24:27], v[178:181]
	v_add_u32_e32 v67, 0, v111
	ds_read_b128 v[222:225], v247 offset:20480
	s_waitcnt vmcnt(9) lgkmcnt(5)
	v_mfma_f32_16x16x32_bf16 v[88:91], v[226:229], v[20:23], v[88:91]
	ds_read_b128 v[226:229], v247 offset:24576
	s_waitcnt lgkmcnt(5)
	v_mfma_f32_16x16x32_bf16 v[92:95], v[230:233], v[20:23], v[92:95]
	ds_read_b128 v[230:233], v247 offset:28672
	s_waitcnt lgkmcnt(5)
	v_mfma_f32_16x16x32_bf16 v[152:155], v[234:237], v[20:23], v[152:155]
	v_add_u32_e32 v248, 0, v113
	ds_read_b128 v[234:237], v248
	s_waitcnt lgkmcnt(5)
	v_mfma_f32_16x16x32_bf16 v[156:159], v[238:241], v[20:23], v[156:159]
	ds_read_b128 v[238:241], v248 offset:4096
	s_waitcnt lgkmcnt(5)
	v_mfma_f32_16x16x32_bf16 v[160:163], v[218:221], v[20:23], v[160:163]
	ds_read_b128 v[218:221], v248 offset:8192
	s_waitcnt lgkmcnt(5)
	v_mfma_f32_16x16x32_bf16 v[164:167], v[222:225], v[20:23], v[164:167]
	ds_read_b128 v[222:225], v248 offset:12288
	s_waitcnt lgkmcnt(5)
	v_mfma_f32_16x16x32_bf16 v[172:175], v[226:229], v[20:23], v[172:175]
	ds_read_b128 v[226:229], v248 offset:16384
	s_waitcnt lgkmcnt(5)
	v_mfma_f32_16x16x32_bf16 v[178:181], v[230:233], v[20:23], v[178:181]
	v_add_u32_e32 v67, 0, v113
	ds_read_b128 v[230:233], v248 offset:20480
	s_waitcnt vmcnt(8) lgkmcnt(5)
	v_mfma_f32_16x16x32_bf16 v[88:91], v[234:237], v[12:15], v[88:91]
	ds_read_b128 v[234:237], v248 offset:24576
	s_waitcnt lgkmcnt(5)
	v_mfma_f32_16x16x32_bf16 v[92:95], v[238:241], v[12:15], v[92:95]
	ds_read_b128 v[238:241], v248 offset:28672
	s_waitcnt lgkmcnt(5)
	v_mfma_f32_16x16x32_bf16 v[152:155], v[218:221], v[12:15], v[152:155]
	s_nop 0
	s_waitcnt lgkmcnt(4)
	v_mfma_f32_16x16x32_bf16 v[156:159], v[222:225], v[12:15], v[156:159]
	s_nop 0
	s_waitcnt lgkmcnt(3)
	v_mfma_f32_16x16x32_bf16 v[160:163], v[226:229], v[12:15], v[160:163]
	s_nop 0
	s_waitcnt lgkmcnt(2)
	v_mfma_f32_16x16x32_bf16 v[164:167], v[230:233], v[12:15], v[164:167]
	s_nop 0
	s_waitcnt lgkmcnt(1)
	v_mfma_f32_16x16x32_bf16 v[172:175], v[234:237], v[12:15], v[172:175]
	s_nop 0
	s_waitcnt lgkmcnt(0)
	v_mfma_f32_16x16x32_bf16 v[178:181], v[238:241], v[12:15], v[178:181]
	v_mov_b32_e32 v67, s6
	ds_read_b32 v67, v67
	s_waitcnt lgkmcnt(0)
; __device__ __forceinline__ unsigned cvt_pk(float lo, float hi) { unsigned r; asm volatile("v_cvt_pk_bf16_f32 %0, %1, %2" : "=v"(r) : "v"(lo), "v"(hi)); return r; }
; __device__ __forceinline__ float bflo(unsigned w) { return __uint_as_float(w << 16); }
; __device__ __forceinline__ float bfhi(unsigned w) { return __uint_as_float(w & 0xffff0000u); }
; template <int SPLIT> __device__ __forceinline__ void scan_item(const Params& p, unsigned char* smem, const int item, const int vh) {
;     ...
;             float rs = 0.f; u32x2 pp[8];
;             const float rowf = __expf(fminf(sc[1] - Ml, 80.f));
; #pragma unroll
;             for (int nb = 0; nb < 8; ++nb) { float pv[4];
; #pragma unroll
;                 for (int jj = 0; jj < 4; ++jj) { const int s = nb * 16 + kq * 4 + jj; pv[jj] = (s <= l) ? acc[nb][jj] * rowf : 0.f; rs += pv[jj]; }
;                 pp[nb].x = cvt_pk(pv[0], pv[1]); pp[nb].y = cvt_pk(pv[2], pv[3]); }
;             __builtin_amdgcn_sched_barrier(0);
;             float nq = 0.f;
; #pragma unroll
;             for (int ks = 0; ks < 4; ++ks) { const f32x4 n0 = *(const f32x4*)(n_s + ks * 32 + kq * 8), n1 = *(const f32x4*)(n_s + ks * 32 + kq * 8 + 4);
;                 const u32x4 qw = *(const u32x4*)&qf[ks];
;                 nq += bflo(qw.x) * n0[0] + bfhi(qw.x) * n0[1] + bflo(qw.y) * n0[2] + bfhi(qw.y) * n0[3] + bflo(qw.z) * n1[0] + bfhi(qw.z) * n1[1] + bflo(qw.w) * n1[2] + bfhi(qw.w) * n1[3]; }
	v_sub_f32_e32 v67, v67, v171
	v_min_f32_e32 v67, 0x42a00000, v67
	v_mul_f32_e32 v67, 0x3fb8aa3b, v67
	v_exp_f32_e32 v87, v67
	s_nop 0
	v_mul_f32_e32 v67, v88, v87
	v_mul_f32_e32 v88, v89, v87
	v_cndmask_b32_e64 v67, v67, 0, s[10:11]
	v_mul_f32_e32 v89, v90, v87
	v_mul_f32_e32 v90, v91, v87
	v_cndmask_b32_e64 v91, 0, v88, s[12:13]
	v_add_f32_e32 v168, 0, v67
	v_cndmask_b32_e64 v89, v89, 0, s[14:15]
	v_cvt_pk_bf16_f32 v88, v67, v91
	v_add_f32_e32 v67, v91, v168
	v_cndmask_b32_e64 v90, v90, 0, s[16:17]
	v_add_f32_e32 v67, v89, v67
	v_add_f32_e32 v67, v90, v67
	v_cvt_pk_bf16_f32 v89, v89, v90
	v_mul_f32_e32 v90, v92, v87
	v_cndmask_b32_e64 v90, v90, 0, s[18:19]
	v_mul_f32_e32 v91, v93, v87
	v_add_f32_e32 v67, v90, v67
	v_cndmask_b32_e64 v91, v91, 0, s[20:21]
	v_mul_f32_e32 v92, v94, v87
	v_add_f32_e32 v67, v91, v67
	v_cndmask_b32_e64 v92, v92, 0, s[22:23]
	v_mul_f32_e32 v93, v95, v87
	v_add_f32_e32 v67, v92, v67
	v_cndmask_b32_e64 v93, v93, 0, s[24:25]
	v_cvt_pk_bf16_f32 v90, v90, v91
	v_cvt_pk_bf16_f32 v91, v92, v93
	v_mul_f32_e32 v92, v152, v87
	v_add_f32_e32 v67, v93, v67
	v_cndmask_b32_e64 v92, v92, 0, s[26:27]
	v_mul_f32_e32 v93, v153, v87
	v_add_f32_e32 v67, v92, v67
	v_cndmask_b32_e64 v93, v93, 0, s[28:29]
	v_mul_f32_e32 v94, v154, v87
	v_add_f32_e32 v67, v93, v67
	v_cndmask_b32_e64 v94, v94, 0, s[30:31]
	v_mul_f32_e32 v95, v155, v87
	v_add_f32_e32 v67, v94, v67
	v_cndmask_b32_e64 v95, v95, 0, s[34:35]
	v_cvt_pk_bf16_f32 v92, v92, v93
	v_cvt_pk_bf16_f32 v93, v94, v95
	v_mul_f32_e32 v94, v156, v87
	v_add_f32_e32 v67, v95, v67
	v_cndmask_b32_e64 v94, v94, 0, s[36:37]
	v_mul_f32_e32 v95, v157, v87
	v_add_f32_e32 v67, v94, v67
	v_cndmask_b32_e64 v95, v95, 0, s[38:39]
	v_mul_f32_e32 v152, v158, v87
	v_add_f32_e32 v67, v95, v67
	v_cndmask_b32_e64 v152, v152, 0, s[40:41]
	v_mul_f32_e32 v153, v159, v87
	v_add_f32_e32 v67, v152, v67
	v_cndmask_b32_e64 v153, v153, 0, s[42:43]
	v_cvt_pk_bf16_f32 v94, v94, v95
	v_cvt_pk_bf16_f32 v95, v152, v153
	v_mul_f32_e32 v152, v160, v87
	v_add_f32_e32 v67, v153, v67
	v_cndmask_b32_e64 v152, v152, 0, s[44:45]
	v_mul_f32_e32 v153, v161, v87
	v_add_f32_e32 v67, v152, v67
	v_cndmask_b32_e64 v153, v153, 0, s[46:47]
	v_mul_f32_e32 v154, v162, v87
	v_add_f32_e32 v67, v153, v67
	v_cndmask_b32_e64 v154, v154, 0, s[48:49]
	v_mul_f32_e32 v155, v163, v87
	v_add_f32_e32 v67, v154, v67
	v_cndmask_b32_e64 v155, v155, 0, s[50:51]
	v_cvt_pk_bf16_f32 v168, v152, v153
	v_mul_f32_e32 v152, v164, v87
	v_add_f32_e32 v67, v155, v67
	v_cndmask_b32_e64 v152, v152, 0, s[52:53]
	v_add_f32_e32 v161, v152, v67
	v_mul_f32_e32 v67, v165, v87
	v_cndmask_b32_e64 v163, v67, 0, s[54:55]
	v_mul_f32_e32 v67, v166, v87
	v_cndmask_b32_e64 v183, v67, 0, s[56:57]
	v_mul_f32_e32 v67, v167, v87
	v_cndmask_b32_e64 v185, v67, 0, s[58:59]
	v_mul_f32_e32 v67, v172, v87
	v_cndmask_b32_e64 v189, v67, 0, s[60:61]
	v_mul_f32_e32 v67, v173, v87
	v_cndmask_b32_e64 v173, v67, 0, s[62:63]
	v_mul_f32_e32 v67, v174, v87
	v_cndmask_b32_e64 v191, v67, 0, s[64:65]
	v_mul_f32_e32 v67, v175, v87
	v_cvt_pk_bf16_f32 v169, v154, v155
	v_cvt_pk_bf16_f32 v186, v152, v163
	v_cndmask_b32_e64 v175, v67, 0, s[66:67]
	v_mul_f32_e32 v67, v178, v87
	v_mul_f32_e32 v152, v179, v87
	v_cndmask_b32_e64 v67, v67, 0, s[68:69]
	v_cndmask_b32_e64 v177, v152, 0, s[70:71]
	v_mul_f32_e32 v152, v180, v87
	v_mul_f32_e32 v87, v181, v87
	v_cvt_pk_bf16_f32 v187, v183, v185
	v_cvt_pk_bf16_f32 v192, v189, v173
	v_cvt_pk_bf16_f32 v193, v191, v175
	v_cndmask_b32_e64 v200, v152, 0, s[72:73]
	v_cndmask_b32_e64 v201, v87, 0, s[74:75]
	v_cvt_pk_bf16_f32 v178, v67, v177
	v_cvt_pk_bf16_f32 v179, v200, v201
	ds_read_b128 v[152:155], v137
	ds_read_b128 v[156:159], v137 offset:16
	v_lshlrev_b32_e32 v87, 16, v28
	v_and_b32_e32 v160, 0xffff0000, v28
	v_and_b32_e32 v195, 0xffff0000, v27
	s_waitcnt lgkmcnt(1)
	v_mul_f32_e32 v162, v152, v87
	v_lshlrev_b32_e32 v87, 16, v29
	v_mul_f32_e32 v182, v154, v87
	v_and_b32_e32 v87, 0xffff0000, v29
	v_mul_f32_e32 v160, v153, v160
	v_mul_f32_e32 v184, v155, v87
	v_lshlrev_b32_e32 v87, 16, v30
	ds_read_b128 v[152:155], v137 offset:128
	s_waitcnt lgkmcnt(1)
	v_mul_f32_e32 v188, v156, v87
	v_and_b32_e32 v87, 0xffff0000, v30
	v_mul_f32_e32 v172, v157, v87
	v_lshlrev_b32_e32 v87, 16, v31
	v_mul_f32_e32 v190, v158, v87
	v_and_b32_e32 v87, 0xffff0000, v31
	v_pk_add_f32 v[180:181], v[162:163], v[160:161]
	v_mul_f32_e32 v174, v159, v87
	ds_read_b128 v[156:159], v137 offset:144
	v_and_b32_e32 v161, 0xffff0000, v24
	v_lshlrev_b32_e32 v160, 16, v24
	s_waitcnt lgkmcnt(1)
	v_mul_f32_e32 v162, v153, v161
	v_pk_fma_f32 v[152:153], v[152:153], v[160:161], v[162:163] op_sel_hi:[1,1,0]
	v_and_b32_e32 v161, 0xffff0000, v25
	v_lshlrev_b32_e32 v160, 16, v25
	v_pk_fma_f32 v[152:153], v[154:155], v[160:161], v[152:153]
	v_mul_f32_e32 v154, v155, v161
	v_pk_add_f32 v[152:153], v[154:155], v[152:153] op_sel_hi:[0,1]
	v_and_b32_e32 v155, 0xffff0000, v26
	v_lshlrev_b32_e32 v154, 16, v26
	s_waitcnt lgkmcnt(0)
	v_pk_fma_f32 v[152:153], v[156:157], v[154:155], v[152:153]
	v_mul_f32_e32 v154, v157, v155
	v_pk_add_f32 v[156:157], v[154:155], v[152:153] op_sel_hi:[0,1]
	ds_read_b128 v[152:155], v137 offset:256
	ds_read_b128 v[160:163], v137 offset:272
	v_lshlrev_b32_e32 v194, 16, v27
	v_and_b32_e32 v165, 0xffff0000, v20
	v_pk_fma_f32 v[156:157], v[158:159], v[194:195], v[156:157]
	v_lshlrev_b32_e32 v164, 16, v20
	s_waitcnt lgkmcnt(1)
	v_mul_f32_e32 v158, v153, v165
	v_pk_fma_f32 v[152:153], v[152:153], v[164:165], v[158:159] op_sel_hi:[1,1,0]
	v_and_b32_e32 v165, 0xffff0000, v21
	v_lshlrev_b32_e32 v164, 16, v21
	v_pk_fma_f32 v[152:153], v[154:155], v[164:165], v[152:153]
	v_mul_f32_e32 v154, v155, v165
	v_pk_add_f32 v[152:153], v[154:155], v[152:153] op_sel_hi:[0,1]
	v_and_b32_e32 v155, 0xffff0000, v22
	v_lshlrev_b32_e32 v154, 16, v22
	s_waitcnt lgkmcnt(0)
; __device__ __forceinline__ float bflo(unsigned w) { return __uint_as_float(w << 16); }
; __device__ __forceinline__ float bfhi(unsigned w) { return __uint_as_float(w & 0xffff0000u); }
; template <int SPLIT> __device__ __forceinline__ void scan_item(const Params& p, unsigned char* smem, const int item, const int vh) {
;     ...
;             for (int ks = 0; ks < 4; ++ks) { const f32x4 n0 = *(const f32x4*)(n_s + ks * 32 + kq * 8), n1 = *(const f32x4*)(n_s + ks * 32 + kq * 8 + 4);
;                 const u32x4 qw = *(const u32x4*)&qf[ks];
;                 nq += bflo(qw.x) * n0[0] + bfhi(qw.x) * n0[1] + bflo(qw.y) * n0[2] + bfhi(qw.y) * n0[3] + bflo(qw.z) * n1[0] + bfhi(qw.z) * n1[1] + bflo(qw.w) * n1[2] + bfhi(qw.w) * n1[3]; }
;             rs += __shfl_xor(rs, 16); rs += __shfl_xor(rs, 32); nq += __shfl_xor(nq, 16); nq += __shfl_xor(nq, 32);
;             const float exl = __expf(m_old - Ml);
;             const float den = rs + exl * nq;
;             const float hinv = __builtin_amdgcn_rcpf(fmaxf(fabsf(den), __expf(-(gl + Ml))));
;             __syncthreads();
; #pragma unroll
;             for (int nb = 0; nb < 8; ++nb) *(u32x2*)(KP + swz(l, nb * 2 + (kq >> 1)) + (kq & 1) * 8) = pp[nb];
;             f32x4 acc2[NBV];
; #pragma unroll
;             for (int nb = 0; nb < NBV; ++nb) acc2[nb] = (f32x4){0.f, 0.f, 0.f, 0.f};
;             __builtin_amdgcn_sched_barrier(0);
;             mm16<NBV>(acc2, CS + vh * 16384, qf, lane);
	v_pk_fma_f32 v[152:153], v[160:161], v[154:155], v[152:153]
	v_mul_f32_e32 v154, v161, v155
	v_pk_add_f32 v[160:161], v[154:155], v[152:153] op_sel_hi:[0,1]
	ds_read_b128 v[152:155], v137 offset:384
	ds_read_b128 v[164:167], v137 offset:400
	v_and_b32_e32 v199, 0xffff0000, v12
	v_lshlrev_b32_e32 v198, 16, v12
	v_and_b32_e32 v197, 0xffff0000, v23
	s_waitcnt lgkmcnt(1)
	v_mul_f32_e32 v158, v153, v199
	v_pk_fma_f32 v[152:153], v[152:153], v[198:199], v[158:159] op_sel_hi:[1,1,0]
	v_and_b32_e32 v199, 0xffff0000, v13
	v_lshlrev_b32_e32 v198, 16, v13
	v_pk_fma_f32 v[152:153], v[154:155], v[198:199], v[152:153]
	v_mul_f32_e32 v154, v155, v199
	v_pk_add_f32 v[152:153], v[154:155], v[152:153] op_sel_hi:[0,1]
	v_and_b32_e32 v155, 0xffff0000, v14
	v_lshlrev_b32_e32 v154, 16, v14
	s_waitcnt lgkmcnt(0)
	v_pk_fma_f32 v[152:153], v[164:165], v[154:155], v[152:153]
	v_mul_f32_e32 v154, v165, v155
	v_pk_add_f32 v[164:165], v[182:183], v[180:181]
	v_pk_add_f32 v[152:153], v[154:155], v[152:153] op_sel_hi:[0,1]
	v_pk_add_f32 v[164:165], v[184:185], v[164:165]
	v_and_b32_e32 v155, 0xffff0000, v15
	v_lshlrev_b32_e32 v154, 16, v15
	v_pk_add_f32 v[164:165], v[188:189], v[164:165]
	v_lshlrev_b32_e32 v196, 16, v23
	v_pk_fma_f32 v[152:153], v[166:167], v[154:155], v[152:153]
	v_and_b32_e32 v154, 64, v150
	v_pk_add_f32 v[164:165], v[172:173], v[164:165]
	v_pk_fma_f32 v[160:161], v[162:163], v[196:197], v[160:161]
	v_add_u32_e32 v162, 64, v154
	v_pk_add_f32 v[164:165], v[190:191], v[164:165]
	v_mul_f32_e32 v154, v159, v195
	v_pk_add_f32 v[164:165], v[174:175], v[164:165]
	v_pk_add_f32 v[156:157], v[154:155], v[156:157] op_sel_hi:[0,1]
	v_mul_f32_e32 v154, v163, v197
	v_xor_b32_e32 v87, 16, v150
	v_pk_add_f32 v[164:165], v[66:67], v[164:165]
	v_mov_b32_e32 v157, v177
	v_pk_add_f32 v[158:159], v[154:155], v[160:161] op_sel_hi:[0,1]
	v_mul_f32_e32 v154, v167, v155
	v_cmp_lt_i32_e32 vcc, v87, v162
	v_pk_add_f32 v[156:157], v[156:157], v[164:165]
	v_mov_b32_e32 v159, v200
	v_pk_add_f32 v[152:153], v[154:155], v[152:153] op_sel_hi:[0,1]
	v_cndmask_b32_e32 v87, v150, v87, vcc
	v_pk_add_f32 v[156:157], v[158:159], v[156:157]
	v_mov_b32_e32 v153, v201
	v_lshlrev_b32_e32 v87, 2, v87
	v_pk_add_f32 v[152:153], v[152:153], v[156:157]
	ds_bpermute_b32 v155, v87, v153
	ds_bpermute_b32 v154, v87, v152
	v_xor_b32_e32 v67, 32, v150
	v_cmp_lt_i32_e32 vcc, v67, v162
	v_sub_f32_e32 v86, v86, v171
	v_mul_f32_e32 v86, 0x3fb8aa3b, v86
	v_cndmask_b32_e32 v67, v150, v67, vcc
	v_lshlrev_b32_e32 v67, 2, v67
	s_waitcnt lgkmcnt(0)
	v_pk_add_f32 v[152:153], v[152:153], v[154:155]
	v_mov_b32_e32 v154, v152
	v_mov_b32_e32 v155, v153
	s_nop 1
	v_permlane32_swap_b32_e32 v154, v152
	v_permlane32_swap_b32_e32 v155, v153
	v_add_f32_e32 v151, v171, v151
	v_exp_f32_e32 v86, v86
	v_mul_f32_e32 v151, 0xbfb8aa3b, v151
	v_exp_f32_e32 v151, v151
	s_waitcnt lgkmcnt(0)
	v_pk_add_f32 v[152:153], v[152:153], v[154:155]
	s_nop 0
	v_fmac_f32_e32 v153, v86, v152
	v_max_f32_e64 v151, |v153|, v151
	s_barrier
	ds_write_b64 v138, v[88:89]
	ds_write_b64 v139, v[90:91]
	ds_write_b64 v140, v[92:93]
	ds_write_b64 v141, v[94:95]
	ds_write_b64 v142, v[168:169]
	ds_write_b64 v143, v[186:187]
	ds_write_b64 v144, v[192:193]
	ds_write_b64 v145, v[178:179]
	v_add_u32_e32 v156, s89, v107
	ds_read_b128 v[88:91], v156
	ds_read_b128 v[92:95], v156 offset:4096
	ds_read_b128 v[152:155], v156 offset:8192
	ds_read_b128 v[156:159], v156 offset:12288
	s_waitcnt lgkmcnt(3)
	v_mfma_f32_16x16x32_bf16 v[88:91], v[88:91], v[28:31], 0
	s_waitcnt lgkmcnt(2)
	v_mfma_f32_16x16x32_bf16 v[92:95], v[92:95], v[28:31], 0
	s_waitcnt lgkmcnt(1)
	v_mfma_f32_16x16x32_bf16 v[152:155], v[152:155], v[28:31], 0
	s_waitcnt lgkmcnt(0)
	v_mfma_f32_16x16x32_bf16 v[28:31], v[156:159], v[28:31], 0
	v_add_u32_e32 v249, s89, v109
	ds_read_b128 v[218:221], v249
	ds_read_b128 v[222:225], v249 offset:4096
	ds_read_b128 v[226:229], v249 offset:8192
	ds_read_b128 v[230:233], v249 offset:12288
	v_add_u32_e32 v160, s89, v109
	s_nop 0
	s_waitcnt lgkmcnt(3)
	v_mfma_f32_16x16x32_bf16 v[88:91], v[218:221], v[24:27], v[88:91]
	s_nop 0
	s_waitcnt lgkmcnt(2)
	v_mfma_f32_16x16x32_bf16 v[92:95], v[222:225], v[24:27], v[92:95]
	s_nop 0
	s_waitcnt lgkmcnt(1)
	v_mfma_f32_16x16x32_bf16 v[152:155], v[226:229], v[24:27], v[152:155]
	s_nop 0
	s_waitcnt lgkmcnt(0)
	v_mfma_f32_16x16x32_bf16 v[24:27], v[230:233], v[24:27], v[28:31]
	v_add_u32_e32 v156, s89, v111
	s_nop 1
	ds_read_b128 v[28:31], v156
	s_waitcnt lgkmcnt(0)
	v_mfma_f32_16x16x32_bf16 v[28:31], v[28:31], v[20:23], v[88:91]
	s_nop 2
	ds_read_b128 v[88:91], v156 offset:4096
	s_waitcnt lgkmcnt(0)
	v_mfma_f32_16x16x32_bf16 v[88:91], v[88:91], v[20:23], v[92:95]
	s_nop 2
	ds_read_b128 v[92:95], v156 offset:8192
	s_waitcnt lgkmcnt(0)
	v_mfma_f32_16x16x32_bf16 v[92:95], v[92:95], v[20:23], v[152:155]
	s_nop 2
	ds_read_b128 v[152:155], v156 offset:12288
	s_waitcnt lgkmcnt(0)
	v_mfma_f32_16x16x32_bf16 v[20:23], v[152:155], v[20:23], v[24:27]
	v_add_u32_e32 v156, s89, v113
	s_nop 1
	ds_read_b128 v[226:229], v156
	ds_read_b128 v[230:233], v156 offset:4096
	ds_read_b128 v[234:237], v156 offset:8192
	ds_read_b128 v[24:27], v156 offset:12288
	s_waitcnt lgkmcnt(3)
	v_mfma_f32_16x16x32_bf16 v[152:155], v[226:229], v[12:15], v[28:31]
	s_nop 0
	s_waitcnt lgkmcnt(2)
	v_mfma_f32_16x16x32_bf16 v[88:91], v[230:233], v[12:15], v[88:91]
	s_nop 0
	s_waitcnt lgkmcnt(1)
	v_mfma_f32_16x16x32_bf16 v[92:95], v[234:237], v[12:15], v[92:95]
	s_nop 0
	s_waitcnt lgkmcnt(0)
; __device__ __forceinline__ unsigned cvt_pk(float lo, float hi) { unsigned r; asm volatile("v_cvt_pk_bf16_f32 %0, %1, %2" : "=v"(r) : "v"(lo), "v"(hi)); return r; }
; #define Q_LOAD(j) do { const size_t r = (size_t)(rfirst + rstep * ((j) * 128 + wid * 16 + li)); \
;           _Pragma("unroll") for (int ks = 0; ks < 4; ++ks) qf[ks] = *(const bf16x8*)(Q0 + r * 512 + h * 128 + ks * 32 + kq * 8); } while (0)
; template <int SPLIT> __device__ __forceinline__ void scan_item(const Params& p, unsigned char* smem, const int item, const int vh) {
;     ...
;             mm16<NBV>(acc2, CS + vh * 16384, qf, lane);
;             __builtin_amdgcn_sched_barrier(0);
;             Q_LOAD(jn);
; #pragma unroll
;             for (int nb = 0; nb < NBV; ++nb) acc2[nb] *= exl;
;             __builtin_amdgcn_sched_barrier(0);
;             { bf16x8 pf[4]; ldfrag(pf, KP, wid, lane); mm16<NBV>(acc2, VT + vh * 16384, pf, lane); }
;             __builtin_amdgcn_sched_barrier(0);
;             { bf16_t* hp = P0 + rowl * LDP + dir * 512 + h * 128 + vh * 64 + kq * 4;
; #pragma unroll
;               for (int nb = 0; nb < NBV; ++nb) { u32x2 o; o.x = cvt_pk(acc2[nb][0] * hinv, acc2[nb][1] * hinv); o.y = cvt_pk(acc2[nb][2] * hinv, acc2[nb][3] * hinv);
;                   *(u32x2*)(hp + nb * 16) = o; } }
;             __builtin_amdgcn_sched_barrier(0);
;             float nnew;
;             { bf16x8 vf[4]; ldfrag(vf, VT, vblk, lane);
; #pragma unroll
;               for (int nb = 0; nb < NBV; ++nb) Cacc[nb] *= decay;
;               mm16<NBV>(Cacc, KT + kh * 16384, vf, lane);
	v_mfma_f32_16x16x32_bf16 v[156:159], v[24:27], v[12:15], v[20:23]
	s_nop 0
	v_add_u32_e32 v12, s0, v96
	v_mul_lo_u32 v12, v12, s3
	v_add_u32_e32 v12, s33, v12
	v_ashrrev_i32_e32 v13, 31, v12
	v_lshlrev_b64 v[12:13], 10, v[12:13]
	v_lshl_add_u64 v[12:13], v[76:77], 0, v[12:13]
	global_load_dwordx4 v[28:31], v[12:13], off
	global_load_dwordx4 v[24:27], v[12:13], off offset:64
	global_load_dwordx4 v[20:23], v[12:13], off offset:128
	s_nop 0
	global_load_dwordx4 v[12:15], v[12:13], off offset:192
	v_pk_mul_f32 v[154:155], v[86:87], v[154:155] op_sel_hi:[0,1]
	v_pk_mul_f32 v[152:153], v[86:87], v[152:153] op_sel_hi:[0,1]
	v_pk_mul_f32 v[90:91], v[86:87], v[90:91] op_sel_hi:[0,1]
	v_pk_mul_f32 v[88:89], v[86:87], v[88:89] op_sel_hi:[0,1]
	v_pk_mul_f32 v[94:95], v[86:87], v[94:95] op_sel_hi:[0,1]
	v_rcp_f32_e32 v151, v151
	v_pk_mul_f32 v[92:93], v[86:87], v[92:93] op_sel_hi:[0,1]
	v_pk_mul_f32 v[158:159], v[86:87], v[158:159] op_sel_hi:[0,1]
	v_pk_mul_f32 v[156:157], v[86:87], v[156:157] op_sel_hi:[0,1]
	v_add_u32_e32 v86, s90, v107
	ds_read_b128 v[160:163], v86 offset:32768
	v_add_u32_e32 v164, v115, v114
	ds_read_b128 v[164:167], v164
	ds_read_b128 v[172:175], v86 offset:36864
	v_add_u32_e32 v168, v116, v114
	ds_read_b128 v[178:181], v168
	s_waitcnt lgkmcnt(1)
	v_mfma_f32_16x16x32_bf16 v[88:91], v[172:175], v[164:167], v[88:91]
	v_add_u32_e32 v168, v118, v114
	ds_read_b128 v[172:175], v86 offset:45056
	v_mfma_f32_16x16x32_bf16 v[152:155], v[160:163], v[164:167], v[152:155]
	ds_read_b128 v[160:163], v86 offset:40960
	v_add_u32_e32 v86, v117, v114
	s_waitcnt lgkmcnt(0)
	v_mfma_f32_16x16x32_bf16 v[92:95], v[160:163], v[164:167], v[92:95]
	ds_read_b128 v[160:163], v86
	ds_read_b128 v[182:185], v168
	v_mfma_f32_16x16x32_bf16 v[156:159], v[172:175], v[164:167], v[156:159]
	v_add_u32_e32 v86, s90, v109
	ds_read_b128 v[226:229], v86 offset:32768
	ds_read_b128 v[230:233], v86 offset:36864
	ds_read_b128 v[234:237], v86 offset:40960
	ds_read_b128 v[164:167], v86 offset:45056
	s_waitcnt lgkmcnt(3)
	v_mfma_f32_16x16x32_bf16 v[152:155], v[226:229], v[178:181], v[152:155]
	s_nop 0
	s_waitcnt lgkmcnt(2)
	v_mfma_f32_16x16x32_bf16 v[88:91], v[230:233], v[178:181], v[88:91]
	s_nop 0
	s_waitcnt lgkmcnt(1)
	v_mfma_f32_16x16x32_bf16 v[92:95], v[234:237], v[178:181], v[92:95]
	s_nop 0
	s_waitcnt lgkmcnt(0)
	v_mfma_f32_16x16x32_bf16 v[156:159], v[164:167], v[178:181], v[156:159]
	s_nop 0
	v_add_u32_e32 v86, s90, v111
	ds_read_b128 v[226:229], v86 offset:32768
	ds_read_b128 v[230:233], v86 offset:36864
	ds_read_b128 v[234:237], v86 offset:40960
	ds_read_b128 v[164:167], v86 offset:45056
	s_waitcnt lgkmcnt(3)
	v_mfma_f32_16x16x32_bf16 v[152:155], v[226:229], v[160:163], v[152:155]
	s_nop 0
	s_waitcnt lgkmcnt(2)
	v_mfma_f32_16x16x32_bf16 v[88:91], v[230:233], v[160:163], v[88:91]
	s_nop 0
	s_waitcnt lgkmcnt(1)
	v_mfma_f32_16x16x32_bf16 v[92:95], v[234:237], v[160:163], v[92:95]
	s_nop 0
	s_waitcnt lgkmcnt(0)
	v_mfma_f32_16x16x32_bf16 v[156:159], v[164:167], v[160:163], v[156:159]
	s_nop 0
	v_add_u32_e32 v250, s90, v113
	ds_read_b128 v[218:221], v250 offset:32768
	ds_read_b128 v[222:225], v250 offset:36864
	ds_read_b128 v[226:229], v250 offset:40960
	ds_read_b128 v[230:233], v250 offset:45056
	v_add_u32_e32 v86, s90, v113
	s_nop 0
	s_waitcnt lgkmcnt(3)
	v_mfma_f32_16x16x32_bf16 v[152:155], v[218:221], v[182:185], v[152:155]
	s_nop 0
	s_waitcnt lgkmcnt(2)
	v_mfma_f32_16x16x32_bf16 v[88:91], v[222:225], v[182:185], v[88:91]
	s_nop 0
	s_waitcnt lgkmcnt(1)
	v_mfma_f32_16x16x32_bf16 v[92:95], v[226:229], v[182:185], v[92:95]
	s_nop 0
	s_waitcnt lgkmcnt(0)
	v_mfma_f32_16x16x32_bf16 v[156:159], v[230:233], v[182:185], v[156:159]
	v_mul_f32_e32 v86, v151, v152
	v_mul_f32_e32 v152, v151, v153
	v_cvt_pk_bf16_f32 v152, v86, v152
	v_mul_f32_e32 v86, v151, v154
	v_mul_f32_e32 v153, v151, v155
	v_mad_i64_i32 v[160:161], s[4:5], v131, s88, v[78:79]
	v_cvt_pk_bf16_f32 v153, v86, v153
	v_mul_f32_e32 v86, v151, v88
	v_mul_f32_e32 v88, v151, v89
	global_store_dwordx2 v[160:161], v[152:153], off
	v_cvt_pk_bf16_f32 v88, v86, v88
	v_mul_f32_e32 v86, v151, v90
	v_mul_f32_e32 v89, v151, v91
	v_cvt_pk_bf16_f32 v89, v86, v89
	global_store_dwordx2 v[160:161], v[88:89], off offset:32
	v_mul_f32_e32 v86, v151, v92
	v_mul_f32_e32 v88, v151, v93
	v_cvt_pk_bf16_f32 v88, v86, v88
	v_mul_f32_e32 v86, v151, v94
	v_mul_f32_e32 v89, v151, v95
	v_cvt_pk_bf16_f32 v89, v86, v89
	global_store_dwordx2 v[160:161], v[88:89], off offset:64
	v_mul_f32_e32 v86, v151, v156
	v_mul_f32_e32 v88, v151, v157
	v_cvt_pk_bf16_f32 v88, v86, v88
	v_mul_f32_e32 v86, v151, v158
	v_mul_f32_e32 v89, v151, v159
	v_cvt_pk_bf16_f32 v89, v86, v89
	global_store_dwordx2 v[160:161], v[88:89], off offset:96
	v_add_u32_e32 v86, v120, v107
	ds_read_b128 v[88:91], v86
	v_add_u32_e32 v92, v115, v119
	ds_read_b128 v[92:95], v92 offset:32768
	ds_read_b128 v[152:155], v86 offset:4096
	v_add_u32_e32 v151, v116, v119
	v_pk_mul_f32 v[50:51], v[50:51], v[84:85] op_sel_hi:[1,0]
	v_pk_mul_f32 v[48:49], v[48:49], v[84:85] op_sel_hi:[1,0]
	ds_read_b128 v[156:159], v151 offset:32768
	ds_read_b128 v[160:163], v86 offset:8192
	v_add_u32_e32 v151, v117, v119
	v_pk_mul_f32 v[54:55], v[54:55], v[84:85] op_sel_hi:[1,0]
	s_waitcnt lgkmcnt(3)
	v_mfma_f32_16x16x32_bf16 v[48:51], v[88:91], v[92:95], v[48:51]
	ds_read_b128 v[88:91], v86 offset:12288
	v_pk_mul_f32 v[52:53], v[52:53], v[84:85] op_sel_hi:[1,0]
	v_pk_mul_f32 v[58:59], v[58:59], v[84:85] op_sel_hi:[1,0]
	v_pk_mul_f32 v[56:57], v[56:57], v[84:85] op_sel_hi:[1,0]
	s_waitcnt lgkmcnt(3)
; __device__ __forceinline__ unsigned cvt_pk(float lo, float hi) { unsigned r; asm volatile("v_cvt_pk_bf16_f32 %0, %1, %2" : "=v"(r) : "v"(lo), "v"(hi)); return r; }
; __device__ __forceinline__ float bflo(unsigned w) { return __uint_as_float(w << 16); }
; __device__ __forceinline__ float bfhi(unsigned w) { return __uint_as_float(w & 0xffff0000u); }
; template <int SPLIT> __device__ __forceinline__ void scan_item(const Params& p, unsigned char* smem, const int item, const int vh) {
;     ...
;               mm16<NBV>(Cacc, KT + kh * 16384, vf, lane);
;               float part = 0.f;
; #pragma unroll
;               for (int ks = 0; ks < 4; ++ks) { const u32x4 kw = *(const u32x4*)(KT + swz(wid * 16 + li, ks * 4 + kq));
;                   part += bflo(kw.x) + bfhi(kw.x) + bflo(kw.y) + bfhi(kw.y) + bflo(kw.z) + bfhi(kw.z) + bflo(kw.w) + bfhi(kw.w); }
;               part += __shfl_xor(part, 16); part += __shfl_xor(part, 32);
;               nnew = decay * n_s[wid * 16 + li] + part; }
;             __syncthreads();
; #pragma unroll
;             for (int nb = 0; nb < NBV; ++nb) { u32x2 o; o.x = cvt_pk(Cacc[nb][0], Cacc[nb][1]); o.y = cvt_pk(Cacc[nb][2], Cacc[nb][3]);
;                 *(u32x2*)(CS + swz(vblk * 16 + li, (kh * 4 + nb) * 2 + (kq >> 1)) + (kq & 1) * 8) = o; }
;             if (kq == 0) n_s[wid * 16 + li] = nnew;
	v_mfma_f32_16x16x32_bf16 v[52:55], v[152:155], v[92:95], v[52:55]
	v_add_u32_e32 v86, v118, v119
	v_pk_mul_f32 v[62:63], v[62:63], v[84:85] op_sel_hi:[1,0]
	v_pk_mul_f32 v[60:61], v[60:61], v[84:85] op_sel_hi:[1,0]
	s_waitcnt lgkmcnt(1)
	v_mfma_f32_16x16x32_bf16 v[56:59], v[160:163], v[92:95], v[56:59]
	ds_read_b128 v[152:155], v151 offset:32768
	ds_read_b128 v[160:163], v86 offset:32768
	s_waitcnt lgkmcnt(2)
	v_mfma_f32_16x16x32_bf16 v[60:63], v[88:91], v[92:95], v[60:63]
	v_add_u32_e32 v251, v120, v109
	ds_read_b128 v[218:221], v251
	ds_read_b128 v[222:225], v251 offset:4096
	ds_read_b128 v[226:229], v251 offset:8192
	ds_read_b128 v[230:233], v251 offset:12288
	v_add_u32_e32 v252, v120, v111
	ds_read_b128 v[234:237], v252
	v_add_u32_e32 v86, v120, v109
	ds_read_b128 v[238:241], v252 offset:4096
	s_waitcnt lgkmcnt(5)
	v_mfma_f32_16x16x32_bf16 v[48:51], v[218:221], v[156:159], v[48:51]
	ds_read_b128 v[218:221], v252 offset:8192
	s_waitcnt lgkmcnt(5)
	v_mfma_f32_16x16x32_bf16 v[52:55], v[222:225], v[156:159], v[52:55]
	ds_read_b128 v[222:225], v252 offset:12288
	s_waitcnt lgkmcnt(5)
	v_mfma_f32_16x16x32_bf16 v[56:59], v[226:229], v[156:159], v[56:59]
	v_add_u32_e32 v253, v120, v113
	ds_read_b128 v[226:229], v253
	s_waitcnt lgkmcnt(5)
	v_mfma_f32_16x16x32_bf16 v[60:63], v[230:233], v[156:159], v[60:63]
	v_add_u32_e32 v86, v120, v111
	ds_read_b128 v[230:233], v253 offset:4096
	s_waitcnt lgkmcnt(5)
	v_mfma_f32_16x16x32_bf16 v[48:51], v[234:237], v[152:155], v[48:51]
	ds_read_b128 v[234:237], v253 offset:8192
	s_waitcnt lgkmcnt(5)
	v_mfma_f32_16x16x32_bf16 v[52:55], v[238:241], v[152:155], v[52:55]
	ds_read_b128 v[238:241], v253 offset:12288
	s_waitcnt lgkmcnt(5)
	v_mfma_f32_16x16x32_bf16 v[56:59], v[218:221], v[152:155], v[56:59]
	s_nop 0
	s_waitcnt lgkmcnt(4)
	v_mfma_f32_16x16x32_bf16 v[60:63], v[222:225], v[152:155], v[60:63]
	v_add_u32_e32 v86, v120, v113
	s_nop 0
	s_waitcnt lgkmcnt(3)
	v_mfma_f32_16x16x32_bf16 v[48:51], v[226:229], v[160:163], v[48:51]
	s_nop 0
	s_waitcnt lgkmcnt(2)
	v_mfma_f32_16x16x32_bf16 v[52:55], v[230:233], v[160:163], v[52:55]
	s_nop 0
	s_waitcnt lgkmcnt(1)
	v_mfma_f32_16x16x32_bf16 v[56:59], v[234:237], v[160:163], v[56:59]
	s_nop 0
	s_waitcnt lgkmcnt(0)
	v_mfma_f32_16x16x32_bf16 v[60:63], v[238:241], v[160:163], v[60:63]
	v_add_u32_e32 v86, v121, v106
	v_add_u32_e32 v242, v121, v108
	v_add_u32_e32 v243, v121, v110
	v_add_u32_e32 v244, v121, v112
	ds_read_b128 v[88:91], v86
	ds_read_b128 v[246:249], v242
	ds_read_b128 v[250:253], v243
	ds_read_b128 v[218:221], v244
	s_waitcnt lgkmcnt(3)
	v_lshlrev_b32_e32 v86, 16, v88
	v_and_b32_e32 v88, 0xffff0000, v88
	v_add_f32_e32 v86, v86, v88
	v_lshlrev_b32_e32 v88, 16, v89
	v_add_f32_e32 v86, v86, v88
	v_and_b32_e32 v88, 0xffff0000, v89
	v_add_f32_e32 v86, v86, v88
	v_lshlrev_b32_e32 v88, 16, v90
	v_add_f32_e32 v86, v86, v88
	v_and_b32_e32 v88, 0xffff0000, v90
	v_add_f32_e32 v86, v86, v88
	v_lshlrev_b32_e32 v88, 16, v91
	v_add_f32_e32 v86, v86, v88
	v_and_b32_e32 v88, 0xffff0000, v91
	v_add_f32_e32 v86, v86, v88
	v_add_f32_e32 v86, 0, v86
	s_waitcnt lgkmcnt(2)
	v_lshlrev_b32_e32 v92, 16, v246
	v_and_b32_e32 v88, 0xffff0000, v246
	v_add_f32_e32 v88, v92, v88
	v_lshlrev_b32_e32 v92, 16, v247
	v_add_f32_e32 v88, v88, v92
	v_and_b32_e32 v89, 0xffff0000, v247
	v_add_f32_e32 v88, v88, v89
	v_lshlrev_b32_e32 v89, 16, v248
	v_add_f32_e32 v88, v88, v89
	v_and_b32_e32 v89, 0xffff0000, v248
	v_add_f32_e32 v88, v88, v89
	v_lshlrev_b32_e32 v89, 16, v249
	v_add_f32_e32 v88, v88, v89
	v_and_b32_e32 v89, 0xffff0000, v249
	v_add_f32_e32 v88, v88, v89
	v_add_f32_e32 v86, v86, v88
	s_waitcnt lgkmcnt(1)
	v_lshlrev_b32_e32 v92, 16, v250
	v_and_b32_e32 v88, 0xffff0000, v250
	v_add_f32_e32 v88, v92, v88
	v_lshlrev_b32_e32 v92, 16, v251
	v_add_f32_e32 v88, v88, v92
	v_and_b32_e32 v89, 0xffff0000, v251
	v_add_f32_e32 v88, v88, v89
	v_lshlrev_b32_e32 v89, 16, v252
	v_add_f32_e32 v88, v88, v89
	v_and_b32_e32 v89, 0xffff0000, v252
	v_add_f32_e32 v88, v88, v89
	v_lshlrev_b32_e32 v89, 16, v253
	v_add_f32_e32 v88, v88, v89
	v_and_b32_e32 v89, 0xffff0000, v253
	v_add_f32_e32 v88, v88, v89
	v_add_f32_e32 v86, v86, v88
	s_waitcnt lgkmcnt(0)
	v_lshlrev_b32_e32 v92, 16, v218
	v_and_b32_e32 v88, 0xffff0000, v218
	v_add_f32_e32 v88, v92, v88
	v_lshlrev_b32_e32 v92, 16, v219
	v_add_f32_e32 v88, v88, v92
	v_and_b32_e32 v89, 0xffff0000, v219
	v_add_f32_e32 v88, v88, v89
	v_lshlrev_b32_e32 v89, 16, v220
	v_add_f32_e32 v88, v88, v89
	v_and_b32_e32 v89, 0xffff0000, v220
	v_add_f32_e32 v88, v88, v89
	v_lshlrev_b32_e32 v89, 16, v221
	v_add_f32_e32 v88, v88, v89
	v_and_b32_e32 v89, 0xffff0000, v221
	v_add_f32_e32 v88, v88, v89
	v_add_f32_e32 v86, v86, v88
	ds_bpermute_b32 v87, v87, v86
	s_waitcnt lgkmcnt(0)
	v_add_f32_e32 v86, v86, v87
	v_mov_b32_e32 v67, v86
	s_nop 1
	v_permlane32_swap_b32_e32 v67, v86
	ds_read_b32 v87, v122
	s_waitcnt lgkmcnt(0)
	s_barrier
	v_cvt_pk_bf16_f32 v88, v48, v49
	v_cvt_pk_bf16_f32 v89, v50, v51
	ds_write_b64 v146, v[88:89]
	v_cvt_pk_bf16_f32 v88, v52, v53
	v_cvt_pk_bf16_f32 v89, v54, v55
	ds_write_b64 v147, v[88:89]
	v_cvt_pk_bf16_f32 v88, v56, v57
	v_cvt_pk_bf16_f32 v89, v58, v59
	ds_write_b64 v148, v[88:89]
	v_cvt_pk_bf16_f32 v88, v60, v61
	v_cvt_pk_bf16_f32 v89, v62, v63
	ds_write_b64 v149, v[88:89]
	s_and_saveexec_b64 s[86:87], s[8:9]
	s_cbranch_execz .LBB0_311
	v_add_f32_e32 v67, v86, v67
	v_fmac_f32_e32 v67, v84, v87
	ds_write_b32 v122, v67
	s_branch .LBB0_311
